# SwiGLU GEMM epilogue: silu chain software-pipelined across element pairs with packed f32 scale/+1 (same per-element op order), hazard nops gone
# baseline (speedup 1.0000x reference)
.LBB0_297:
	s_add_u32 s22, s20, 0xfffc0080
	s_addc_u32 s23, s21, -1
	s_add_i32 s49, 0, 0x10000
	v_add_u32_e32 v145, s49, v142
	ds_read_b128 v[146:149], v145
	ds_read_b128 v[150:153], v145 offset:1024
	ds_read_b128 v[154:157], v145 offset:2048
	ds_read_b128 v[158:161], v145 offset:3072
	s_cmp_eq_u32 s48, 12
	s_cselect_b32 s25, s9, s23
	s_cselect_b32 s24, s44, s22
	s_cselect_b32 s23, s7, s47
	s_cselect_b32 s22, s45, s46
	s_add_i32 m0, s19, 0xc000
	ds_read_b128 v[162:165], v144
	ds_read_b128 v[166:169], v144 offset:1024
	ds_read_b128 v[170:173], v144 offset:2048
	ds_read_b128 v[174:177], v144 offset:3072
	ds_read_b128 v[190:193], v144 offset:4096
	ds_read_b128 v[194:197], v144 offset:5120
	ds_read_b128 v[198:201], v144 offset:6144
	ds_read_b128 v[202:205], v144 offset:7168
	global_load_lds_dwordx4 v138, s[20:21]
	s_add_i32 m0, s19, 0xe000
	s_nop 0
	global_load_lds_dwordx4 v140, s[20:21]
	s_waitcnt lgkmcnt(8)
	s_barrier
	s_waitcnt lgkmcnt(0)
	s_waitcnt lgkmcnt(0)
	v_mfma_f32_16x16x32_bf16 v[126:129], v[146:149], v[162:165], v[126:129]
	v_mfma_f32_16x16x32_bf16 v[118:121], v[154:157], v[162:165], v[118:121]
	v_mfma_f32_16x16x32_bf16 v[110:113], v[146:149], v[170:173], v[110:113]
	v_mfma_f32_16x16x32_bf16 v[102:105], v[154:157], v[170:173], v[102:105]
	v_mfma_f32_16x16x32_bf16 v[94:97], v[146:149], v[190:193], v[94:97]
	v_mfma_f32_16x16x32_bf16 v[86:89], v[154:157], v[190:193], v[86:89]
	v_mfma_f32_16x16x32_bf16 v[78:81], v[146:149], v[198:201], v[78:81]
	v_mfma_f32_16x16x32_bf16 v[70:73], v[154:157], v[198:201], v[70:73]
	v_mfma_f32_16x16x32_bf16 v[126:129], v[150:153], v[166:169], v[126:129]
	v_mfma_f32_16x16x32_bf16 v[118:121], v[158:161], v[166:169], v[118:121]
	v_mfma_f32_16x16x32_bf16 v[110:113], v[150:153], v[174:177], v[110:113]
	v_mfma_f32_16x16x32_bf16 v[102:105], v[158:161], v[174:177], v[102:105]
	v_mfma_f32_16x16x32_bf16 v[94:97], v[150:153], v[194:197], v[94:97]
	v_mfma_f32_16x16x32_bf16 v[86:89], v[158:161], v[194:197], v[86:89]
	v_mfma_f32_16x16x32_bf16 v[78:81], v[150:153], v[202:205], v[78:81]
	v_mfma_f32_16x16x32_bf16 v[70:73], v[158:161], v[202:205], v[70:73]
	s_barrier
	s_add_i32 s54, 0, 0x14000
	s_add_i32 s49, s49, s35
	v_add_u32_e32 v145, s54, v142
	s_add_u32 s64, s22, 0x80
	s_addc_u32 s65, s23, 0
	s_mov_b32 m0, s49
	ds_read_b128 v[206:209], v145
	ds_read_b128 v[210:213], v145 offset:1024
	ds_read_b128 v[214:217], v145 offset:2048
	ds_read_b128 v[218:221], v145 offset:3072
	global_load_lds_dwordx4 v134, s[22:23]
	s_add_i32 m0, s49, 0x2000
	s_nop 0
	global_load_lds_dwordx4 v130, s[22:23]
	s_barrier
	s_waitcnt lgkmcnt(0)
	s_waitcnt lgkmcnt(0)
	v_mfma_f32_16x16x32_bf16 v[122:125], v[206:209], v[162:165], v[122:125]
	v_mfma_f32_16x16x32_bf16 v[114:117], v[214:217], v[162:165], v[114:117]
	v_mfma_f32_16x16x32_bf16 v[106:109], v[206:209], v[170:173], v[106:109]
	v_mfma_f32_16x16x32_bf16 v[98:101], v[214:217], v[170:173], v[98:101]
	v_mfma_f32_16x16x32_bf16 v[90:93], v[206:209], v[190:193], v[90:93]
	v_mfma_f32_16x16x32_bf16 v[82:85], v[214:217], v[190:193], v[82:85]
	v_mfma_f32_16x16x32_bf16 v[74:77], v[206:209], v[198:201], v[74:77]
	v_mfma_f32_16x16x32_bf16 v[66:69], v[214:217], v[198:201], v[66:69]
	v_mfma_f32_16x16x32_bf16 v[122:125], v[210:213], v[166:169], v[122:125]
	v_mfma_f32_16x16x32_bf16 v[114:117], v[218:221], v[166:169], v[114:117]
	v_mfma_f32_16x16x32_bf16 v[106:109], v[210:213], v[174:177], v[106:109]
	v_mfma_f32_16x16x32_bf16 v[98:101], v[218:221], v[174:177], v[98:101]
	v_mfma_f32_16x16x32_bf16 v[90:93], v[210:213], v[194:197], v[90:93]
	v_mfma_f32_16x16x32_bf16 v[82:85], v[218:221], v[194:197], v[82:85]
	v_mfma_f32_16x16x32_bf16 v[74:77], v[210:213], v[202:205], v[74:77]
	v_mfma_f32_16x16x32_bf16 v[66:69], v[218:221], v[202:205], v[66:69]
	s_barrier
	s_mov_b32 m0, s19
	s_add_u32 s62, s24, 0x80
	s_addc_u32 s63, s25, 0
	ds_read_b128 v[162:165], v144 offset:16384
	ds_read_b128 v[166:169], v144 offset:17408
	ds_read_b128 v[170:173], v144 offset:18432
	ds_read_b128 v[174:177], v144 offset:19456
	ds_read_b128 v[190:193], v144 offset:20480
	ds_read_b128 v[194:197], v144 offset:21504
	ds_read_b128 v[198:201], v144 offset:22528
	ds_read_b128 v[202:205], v144 offset:23552
	global_load_lds_dwordx4 v136, s[24:25]
	s_mov_b32 m0, s36
	s_nop 0
	global_load_lds_dwordx4 v132, s[24:25]
	s_barrier
	s_waitcnt lgkmcnt(0)
	s_waitcnt lgkmcnt(0)
	v_mfma_f32_16x16x32_bf16 v[62:65], v[146:149], v[162:165], v[62:65]
	v_mfma_f32_16x16x32_bf16 v[54:57], v[154:157], v[162:165], v[54:57]
	v_mfma_f32_16x16x32_bf16 v[46:49], v[146:149], v[170:173], v[46:49]
	v_mfma_f32_16x16x32_bf16 v[38:41], v[154:157], v[170:173], v[38:41]
	v_mfma_f32_16x16x32_bf16 v[30:33], v[146:149], v[190:193], v[30:33]
	v_mfma_f32_16x16x32_bf16 v[22:25], v[154:157], v[190:193], v[22:25]
	v_mfma_f32_16x16x32_bf16 v[14:17], v[146:149], v[198:201], v[14:17]
	v_mfma_f32_16x16x32_bf16 v[6:9], v[154:157], v[198:201], v[6:9]
	v_mfma_f32_16x16x32_bf16 v[62:65], v[150:153], v[166:169], v[62:65]
	v_mfma_f32_16x16x32_bf16 v[54:57], v[158:161], v[166:169], v[54:57]
	v_mfma_f32_16x16x32_bf16 v[46:49], v[150:153], v[174:177], v[46:49]
	v_mfma_f32_16x16x32_bf16 v[38:41], v[158:161], v[174:177], v[38:41]
	v_mfma_f32_16x16x32_bf16 v[30:33], v[150:153], v[194:197], v[30:33]
	v_mfma_f32_16x16x32_bf16 v[22:25], v[158:161], v[194:197], v[22:25]
	v_mfma_f32_16x16x32_bf16 v[14:17], v[150:153], v[202:205], v[14:17]
	v_mfma_f32_16x16x32_bf16 v[6:9], v[158:161], v[202:205], v[6:9]
	s_barrier
	s_add_u32 s50, s22, 0x40000
	s_addc_u32 s51, s23, 0
	s_add_i32 s49, s54, s35
	s_mov_b32 m0, s49
	s_nop 0
	global_load_lds_dwordx4 v134, s[50:51]
	s_add_i32 m0, s49, 0x2000
	s_nop 0
	global_load_lds_dwordx4 v130, s[50:51]
	s_waitcnt vmcnt(6)
	s_barrier
	v_mfma_f32_16x16x32_bf16 v[58:61], v[206:209], v[162:165], v[58:61]
	v_mfma_f32_16x16x32_bf16 v[50:53], v[214:217], v[162:165], v[50:53]
	v_mfma_f32_16x16x32_bf16 v[42:45], v[206:209], v[170:173], v[42:45]
	v_mfma_f32_16x16x32_bf16 v[34:37], v[214:217], v[170:173], v[34:37]
	v_mfma_f32_16x16x32_bf16 v[26:29], v[206:209], v[190:193], v[26:29]
	v_mfma_f32_16x16x32_bf16 v[18:21], v[214:217], v[190:193], v[18:21]
	v_mfma_f32_16x16x32_bf16 v[10:13], v[206:209], v[198:201], v[10:13]
	v_mfma_f32_16x16x32_bf16 v[2:5], v[214:217], v[198:201], v[2:5]
	v_mfma_f32_16x16x32_bf16 v[58:61], v[210:213], v[166:169], v[58:61]
	v_mfma_f32_16x16x32_bf16 v[50:53], v[218:221], v[166:169], v[50:53]
	v_mfma_f32_16x16x32_bf16 v[42:45], v[210:213], v[174:177], v[42:45]
	v_mfma_f32_16x16x32_bf16 v[34:37], v[218:221], v[174:177], v[34:37]
	v_mfma_f32_16x16x32_bf16 v[26:29], v[210:213], v[194:197], v[26:29]
	v_mfma_f32_16x16x32_bf16 v[18:21], v[218:221], v[194:197], v[18:21]
	v_mfma_f32_16x16x32_bf16 v[10:13], v[210:213], v[202:205], v[10:13]
	v_mfma_f32_16x16x32_bf16 v[2:5], v[218:221], v[202:205], v[2:5]
	s_barrier
	s_add_i32 s49, 0, 0x18000
	v_add_u32_e32 v145, s49, v142
	ds_read_b128 v[146:149], v145
	ds_read_b128 v[150:153], v145 offset:1024
	ds_read_b128 v[154:157], v145 offset:2048
	ds_read_b128 v[158:161], v145 offset:3072
	s_add_u32 s24, s24, 0x40000
	s_addc_u32 s25, s25, 0
	s_mov_b32 m0, s37
	ds_read_b128 v[162:165], v144 offset:32768
	ds_read_b128 v[166:169], v144 offset:33792
	ds_read_b128 v[170:173], v144 offset:34816
	ds_read_b128 v[174:177], v144 offset:35840
	ds_read_b128 v[190:193], v144 offset:36864
	ds_read_b128 v[194:197], v144 offset:37888
	ds_read_b128 v[198:201], v144 offset:38912
	ds_read_b128 v[202:205], v144 offset:39936
	global_load_lds_dwordx4 v136, s[24:25]
	s_mov_b32 m0, s38
	s_nop 0
	global_load_lds_dwordx4 v132, s[24:25]
	s_waitcnt lgkmcnt(8)
	s_barrier
	s_waitcnt lgkmcnt(0)
	s_waitcnt lgkmcnt(0)
	v_mfma_f32_16x16x32_bf16 v[126:129], v[146:149], v[162:165], v[126:129]
	v_mfma_f32_16x16x32_bf16 v[118:121], v[154:157], v[162:165], v[118:121]
	v_mfma_f32_16x16x32_bf16 v[110:113], v[146:149], v[170:173], v[110:113]
	v_mfma_f32_16x16x32_bf16 v[102:105], v[154:157], v[170:173], v[102:105]
	v_mfma_f32_16x16x32_bf16 v[94:97], v[146:149], v[190:193], v[94:97]
	v_mfma_f32_16x16x32_bf16 v[86:89], v[154:157], v[190:193], v[86:89]
	v_mfma_f32_16x16x32_bf16 v[78:81], v[146:149], v[198:201], v[78:81]
	v_mfma_f32_16x16x32_bf16 v[70:73], v[154:157], v[198:201], v[70:73]
	v_mfma_f32_16x16x32_bf16 v[126:129], v[150:153], v[166:169], v[126:129]
	v_mfma_f32_16x16x32_bf16 v[118:121], v[158:161], v[166:169], v[118:121]
	v_mfma_f32_16x16x32_bf16 v[110:113], v[150:153], v[174:177], v[110:113]
	v_mfma_f32_16x16x32_bf16 v[102:105], v[158:161], v[174:177], v[102:105]
	v_mfma_f32_16x16x32_bf16 v[94:97], v[150:153], v[194:197], v[94:97]
	v_mfma_f32_16x16x32_bf16 v[86:89], v[158:161], v[194:197], v[86:89]
	v_mfma_f32_16x16x32_bf16 v[78:81], v[150:153], v[202:205], v[78:81]
	v_mfma_f32_16x16x32_bf16 v[70:73], v[158:161], v[202:205], v[70:73]
	s_barrier
	s_add_i32 s24, 0, 0x1c000
	s_add_i32 s25, s49, s35
	v_add_u32_e32 v145, s24, v142
	s_mov_b32 m0, s25
	ds_read_b128 v[206:209], v145
	ds_read_b128 v[210:213], v145 offset:1024
	ds_read_b128 v[214:217], v145 offset:2048
	ds_read_b128 v[218:221], v145 offset:3072
	global_load_lds_dwordx4 v134, s[64:65]
	s_add_i32 m0, s25, 0x2000
	s_nop 0
	global_load_lds_dwordx4 v130, s[64:65]
	s_barrier
	s_waitcnt lgkmcnt(0)
	s_waitcnt lgkmcnt(0)
	v_mfma_f32_16x16x32_bf16 v[122:125], v[206:209], v[162:165], v[122:125]
	v_mfma_f32_16x16x32_bf16 v[114:117], v[214:217], v[162:165], v[114:117]
	v_mfma_f32_16x16x32_bf16 v[106:109], v[206:209], v[170:173], v[106:109]
	v_mfma_f32_16x16x32_bf16 v[98:101], v[214:217], v[170:173], v[98:101]
	v_mfma_f32_16x16x32_bf16 v[90:93], v[206:209], v[190:193], v[90:93]
	v_mfma_f32_16x16x32_bf16 v[82:85], v[214:217], v[190:193], v[82:85]
	v_mfma_f32_16x16x32_bf16 v[74:77], v[206:209], v[198:201], v[74:77]
	v_mfma_f32_16x16x32_bf16 v[66:69], v[214:217], v[198:201], v[66:69]
	v_mfma_f32_16x16x32_bf16 v[122:125], v[210:213], v[166:169], v[122:125]
	v_mfma_f32_16x16x32_bf16 v[114:117], v[218:221], v[166:169], v[114:117]
	v_mfma_f32_16x16x32_bf16 v[106:109], v[210:213], v[174:177], v[106:109]
	v_mfma_f32_16x16x32_bf16 v[98:101], v[218:221], v[174:177], v[98:101]
	v_mfma_f32_16x16x32_bf16 v[90:93], v[210:213], v[194:197], v[90:93]
	v_mfma_f32_16x16x32_bf16 v[82:85], v[218:221], v[194:197], v[82:85]
	v_mfma_f32_16x16x32_bf16 v[74:77], v[210:213], v[202:205], v[74:77]
	v_mfma_f32_16x16x32_bf16 v[66:69], v[218:221], v[202:205], v[66:69]
	s_barrier
	s_mov_b32 m0, s39
	ds_read_b128 v[162:165], v144 offset:49152
	ds_read_b128 v[166:169], v144 offset:50176
	ds_read_b128 v[170:173], v144 offset:51200
	ds_read_b128 v[174:177], v144 offset:52224
	ds_read_b128 v[190:193], v144 offset:53248
	ds_read_b128 v[194:197], v144 offset:54272
	ds_read_b128 v[198:201], v144 offset:55296
	ds_read_b128 v[202:205], v144 offset:56320
	global_load_lds_dwordx4 v136, s[62:63]
	s_mov_b32 m0, s40
	s_nop 0
	global_load_lds_dwordx4 v132, s[62:63]
	s_barrier
	s_waitcnt lgkmcnt(0)
	s_waitcnt lgkmcnt(0)
	v_mfma_f32_16x16x32_bf16 v[62:65], v[146:149], v[162:165], v[62:65]
	v_mfma_f32_16x16x32_bf16 v[54:57], v[154:157], v[162:165], v[54:57]
	v_mfma_f32_16x16x32_bf16 v[46:49], v[146:149], v[170:173], v[46:49]
	v_mfma_f32_16x16x32_bf16 v[38:41], v[154:157], v[170:173], v[38:41]
	v_mfma_f32_16x16x32_bf16 v[30:33], v[146:149], v[190:193], v[30:33]
	v_mfma_f32_16x16x32_bf16 v[22:25], v[154:157], v[190:193], v[22:25]
	v_mfma_f32_16x16x32_bf16 v[14:17], v[146:149], v[198:201], v[14:17]
	v_mfma_f32_16x16x32_bf16 v[6:9], v[154:157], v[198:201], v[6:9]
	v_mfma_f32_16x16x32_bf16 v[62:65], v[150:153], v[166:169], v[62:65]
	v_mfma_f32_16x16x32_bf16 v[54:57], v[158:161], v[166:169], v[54:57]
	v_mfma_f32_16x16x32_bf16 v[46:49], v[150:153], v[174:177], v[46:49]
	v_mfma_f32_16x16x32_bf16 v[38:41], v[158:161], v[174:177], v[38:41]
	v_mfma_f32_16x16x32_bf16 v[30:33], v[150:153], v[194:197], v[30:33]
	v_mfma_f32_16x16x32_bf16 v[22:25], v[158:161], v[194:197], v[22:25]
	v_mfma_f32_16x16x32_bf16 v[14:17], v[150:153], v[202:205], v[14:17]
	v_mfma_f32_16x16x32_bf16 v[6:9], v[158:161], v[202:205], v[6:9]
	s_barrier
	s_add_u32 s22, s22, 0x40080
	s_addc_u32 s23, s23, 0
	s_add_i32 s24, s24, s35
	s_mov_b32 m0, s24
	s_nop 0
	global_load_lds_dwordx4 v134, s[22:23]
	s_add_i32 m0, s24, 0x2000
	s_nop 0
	global_load_lds_dwordx4 v130, s[22:23]
	s_waitcnt vmcnt(6)
	s_barrier
	v_mfma_f32_16x16x32_bf16 v[58:61], v[206:209], v[162:165], v[58:61]
	v_mfma_f32_16x16x32_bf16 v[50:53], v[214:217], v[162:165], v[50:53]
	v_mfma_f32_16x16x32_bf16 v[42:45], v[206:209], v[170:173], v[42:45]
	v_mfma_f32_16x16x32_bf16 v[34:37], v[214:217], v[170:173], v[34:37]
	v_mfma_f32_16x16x32_bf16 v[26:29], v[206:209], v[190:193], v[26:29]
	v_mfma_f32_16x16x32_bf16 v[18:21], v[214:217], v[190:193], v[18:21]
	v_mfma_f32_16x16x32_bf16 v[10:13], v[206:209], v[198:201], v[10:13]
	v_mfma_f32_16x16x32_bf16 v[2:5], v[214:217], v[198:201], v[2:5]
	v_mfma_f32_16x16x32_bf16 v[58:61], v[210:213], v[166:169], v[58:61]
	v_mfma_f32_16x16x32_bf16 v[50:53], v[218:221], v[166:169], v[50:53]
	v_mfma_f32_16x16x32_bf16 v[42:45], v[210:213], v[174:177], v[42:45]
	v_mfma_f32_16x16x32_bf16 v[34:37], v[218:221], v[174:177], v[34:37]
	v_mfma_f32_16x16x32_bf16 v[26:29], v[210:213], v[194:197], v[26:29]
	v_mfma_f32_16x16x32_bf16 v[18:21], v[218:221], v[194:197], v[18:21]
	v_mfma_f32_16x16x32_bf16 v[10:13], v[210:213], v[202:205], v[10:13]
	v_mfma_f32_16x16x32_bf16 v[2:5], v[218:221], v[202:205], v[2:5]
	s_barrier
	s_add_i32 s48, s48, 2
	s_add_u32 s20, s20, 0x100
	s_addc_u32 s21, s21, 0
	s_add_u32 s46, s46, 0x100
	s_addc_u32 s47, s47, 0
	s_cmp_gt_u32 s48, 13
	s_cbranch_scc0 .LBB0_297
	v_mov_b32_e32 v226, 0xbfb8aa3b
	v_mov_b32_e32 v227, 0xbfb8aa3b
	v_mov_b32_e32 v228, 1.0
	v_mov_b32_e32 v229, 1.0
	v_pk_mul_f32 v[222:223], v[126:127], v[226:227]
	v_exp_f32_e32 v222, v222
	v_exp_f32_e32 v223, v223
	s_nop 0
	v_pk_add_f32 v[222:223], v[222:223], v[228:229]
	v_rcp_f32_e32 v222, v222
	v_rcp_f32_e32 v223, v223
	v_pk_mul_f32 v[224:225], v[128:129], v[226:227]
	v_exp_f32_e32 v224, v224
	v_exp_f32_e32 v225, v225
	v_pk_mul_f32 v[222:223], v[126:127], v[222:223]
	v_pk_add_f32 v[224:225], v[224:225], v[228:229]
	v_rcp_f32_e32 v224, v224
	v_rcp_f32_e32 v225, v225
	v_pk_mul_f32 v[122:123], v[222:223], v[122:123]
	v_pk_mul_f32 v[222:223], v[118:119], v[226:227]
	v_exp_f32_e32 v222, v222
	v_exp_f32_e32 v223, v223
	v_pk_mul_f32 v[224:225], v[128:129], v[224:225]
	v_pk_add_f32 v[222:223], v[222:223], v[228:229]
	v_rcp_f32_e32 v222, v222
	v_rcp_f32_e32 v223, v223
	v_pk_mul_f32 v[124:125], v[224:225], v[124:125]
	v_pk_mul_f32 v[224:225], v[120:121], v[226:227]
	v_exp_f32_e32 v224, v224
	v_exp_f32_e32 v225, v225
	v_pk_mul_f32 v[222:223], v[118:119], v[222:223]
	v_pk_add_f32 v[224:225], v[224:225], v[228:229]
	v_rcp_f32_e32 v224, v224
	v_rcp_f32_e32 v225, v225
	v_pk_mul_f32 v[114:115], v[222:223], v[114:115]
	v_pk_mul_f32 v[222:223], v[110:111], v[226:227]
	v_exp_f32_e32 v222, v222
	v_exp_f32_e32 v223, v223
	v_pk_mul_f32 v[224:225], v[120:121], v[224:225]
	v_pk_add_f32 v[222:223], v[222:223], v[228:229]
	v_rcp_f32_e32 v222, v222
	v_rcp_f32_e32 v223, v223
	v_pk_mul_f32 v[116:117], v[224:225], v[116:117]
	v_lshl_or_b32 v146, s43, 7, v143
	v_lshl_add_u32 v145, s18, 8, v1
	v_ashrrev_i32_e32 v147, 31, v146
	s_movk_i32 s7, 0x1700
	s_and_b64 vcc, exec, s[4:5]
	s_mov_b32 s43, s6
	s_mov_b32 s18, s8
	s_mov_b64 s[22:23], s[14:15]
	v_cvt_pk_bf16_f32 v120, v114, v115
	v_mov_b64_e32 v[114:115], s[2:3]
	v_cvt_pk_bf16_f32 v118, v122, v123
	v_cvt_pk_bf16_f32 v121, v116, v117
	v_mad_i64_i32 v[122:123], s[20:21], v145, s7, v[114:115]
	v_lshlrev_b64 v[116:117], 1, v[146:147]
	v_cvt_pk_bf16_f32 v119, v124, v125
	v_lshl_add_u64 v[122:123], v[122:123], 0, v[116:117]
	global_store_dwordx4 v[122:123], v[118:121], off
	s_nop 1
	v_pk_mul_f32 v[224:225], v[112:113], v[226:227]
	v_exp_f32_e32 v224, v224
	v_exp_f32_e32 v225, v225
	v_pk_mul_f32 v[222:223], v[110:111], v[222:223]
	v_pk_add_f32 v[224:225], v[224:225], v[228:229]
	v_rcp_f32_e32 v224, v224
	v_rcp_f32_e32 v225, v225
	v_pk_mul_f32 v[106:107], v[222:223], v[106:107]
	v_pk_mul_f32 v[222:223], v[102:103], v[226:227]
	v_exp_f32_e32 v222, v222
	v_exp_f32_e32 v223, v223
	v_pk_mul_f32 v[224:225], v[112:113], v[224:225]
	v_pk_add_f32 v[222:223], v[222:223], v[228:229]
	v_rcp_f32_e32 v222, v222
	v_rcp_f32_e32 v223, v223
	v_pk_mul_f32 v[108:109], v[224:225], v[108:109]
	v_pk_mul_f32 v[224:225], v[104:105], v[226:227]
	v_exp_f32_e32 v224, v224
	v_exp_f32_e32 v225, v225
	v_pk_mul_f32 v[222:223], v[102:103], v[222:223]
	v_pk_add_f32 v[224:225], v[224:225], v[228:229]
	v_rcp_f32_e32 v224, v224
	v_rcp_f32_e32 v225, v225
	v_pk_mul_f32 v[102:103], v[222:223], v[98:99]
	v_pk_mul_f32 v[222:223], v[94:95], v[226:227]
	v_exp_f32_e32 v222, v222
	v_exp_f32_e32 v223, v223
	v_pk_mul_f32 v[224:225], v[104:105], v[224:225]
	v_pk_add_f32 v[222:223], v[222:223], v[228:229]
	v_rcp_f32_e32 v222, v222
	v_rcp_f32_e32 v223, v223
	v_pk_mul_f32 v[104:105], v[224:225], v[100:101]
	v_cvt_pk_bf16_f32 v100, v102, v103
	v_or_b32_e32 v102, 16, v145
	v_mad_i64_i32 v[102:103], s[20:21], v102, s7, v[114:115]
	v_cvt_pk_bf16_f32 v98, v106, v107
	v_cvt_pk_bf16_f32 v99, v108, v109
	v_cvt_pk_bf16_f32 v101, v104, v105
	v_lshl_add_u64 v[102:103], v[102:103], 0, v[116:117]
	global_store_dwordx4 v[102:103], v[98:101], off
	s_nop 1
	v_pk_mul_f32 v[224:225], v[96:97], v[226:227]
	v_exp_f32_e32 v224, v224
	v_exp_f32_e32 v225, v225
	v_pk_mul_f32 v[222:223], v[94:95], v[222:223]
	v_pk_add_f32 v[224:225], v[224:225], v[228:229]
	v_rcp_f32_e32 v224, v224
	v_rcp_f32_e32 v225, v225
	v_pk_mul_f32 v[90:91], v[222:223], v[90:91]
	v_pk_mul_f32 v[222:223], v[86:87], v[226:227]
	v_exp_f32_e32 v222, v222
	v_exp_f32_e32 v223, v223
	v_pk_mul_f32 v[224:225], v[96:97], v[224:225]
	v_pk_add_f32 v[222:223], v[222:223], v[228:229]
	v_rcp_f32_e32 v222, v222
	v_rcp_f32_e32 v223, v223
	v_pk_mul_f32 v[92:93], v[224:225], v[92:93]
	v_pk_mul_f32 v[224:225], v[88:89], v[226:227]
	v_exp_f32_e32 v224, v224
	v_exp_f32_e32 v225, v225
	v_pk_mul_f32 v[222:223], v[86:87], v[222:223]
	v_pk_add_f32 v[224:225], v[224:225], v[228:229]
	v_rcp_f32_e32 v224, v224
	v_rcp_f32_e32 v225, v225
	v_pk_mul_f32 v[86:87], v[222:223], v[82:83]
	v_pk_mul_f32 v[222:223], v[78:79], v[226:227]
	v_exp_f32_e32 v222, v222
	v_exp_f32_e32 v223, v223
	v_pk_mul_f32 v[224:225], v[88:89], v[224:225]
	v_pk_add_f32 v[222:223], v[222:223], v[228:229]
	v_rcp_f32_e32 v222, v222
	v_rcp_f32_e32 v223, v223
	v_pk_mul_f32 v[88:89], v[224:225], v[84:85]
	v_cvt_pk_bf16_f32 v84, v86, v87
	v_or_b32_e32 v86, 32, v145
	v_mad_i64_i32 v[86:87], s[20:21], v86, s7, v[114:115]
	v_cvt_pk_bf16_f32 v82, v90, v91
	v_cvt_pk_bf16_f32 v83, v92, v93
	v_cvt_pk_bf16_f32 v85, v88, v89
	v_lshl_add_u64 v[86:87], v[86:87], 0, v[116:117]
	global_store_dwordx4 v[86:87], v[82:85], off
	s_nop 1
	v_pk_mul_f32 v[224:225], v[80:81], v[226:227]
	v_exp_f32_e32 v224, v224
	v_exp_f32_e32 v225, v225
	v_pk_mul_f32 v[222:223], v[78:79], v[222:223]
	v_pk_add_f32 v[224:225], v[224:225], v[228:229]
	v_rcp_f32_e32 v224, v224
	v_rcp_f32_e32 v225, v225
	v_pk_mul_f32 v[74:75], v[222:223], v[74:75]
	v_pk_mul_f32 v[222:223], v[70:71], v[226:227]
	v_exp_f32_e32 v222, v222
	v_exp_f32_e32 v223, v223
	v_pk_mul_f32 v[224:225], v[80:81], v[224:225]
	v_pk_add_f32 v[222:223], v[222:223], v[228:229]
	v_rcp_f32_e32 v222, v222
	v_rcp_f32_e32 v223, v223
	v_pk_mul_f32 v[76:77], v[224:225], v[76:77]
	v_pk_mul_f32 v[224:225], v[72:73], v[226:227]
	v_exp_f32_e32 v224, v224
	v_exp_f32_e32 v225, v225
	v_pk_mul_f32 v[222:223], v[70:71], v[222:223]
	v_pk_add_f32 v[224:225], v[224:225], v[228:229]
	v_rcp_f32_e32 v224, v224
	v_rcp_f32_e32 v225, v225
	v_pk_mul_f32 v[70:71], v[222:223], v[66:67]
	v_pk_mul_f32 v[222:223], v[62:63], v[226:227]
	v_exp_f32_e32 v222, v222
	v_exp_f32_e32 v223, v223
	v_pk_mul_f32 v[224:225], v[72:73], v[224:225]
	v_pk_add_f32 v[222:223], v[222:223], v[228:229]
	v_rcp_f32_e32 v222, v222
	v_rcp_f32_e32 v223, v223
	v_pk_mul_f32 v[72:73], v[224:225], v[68:69]
	v_cvt_pk_bf16_f32 v68, v70, v71
	v_or_b32_e32 v70, 48, v145
	v_mad_i64_i32 v[70:71], s[20:21], v70, s7, v[114:115]
	v_cvt_pk_bf16_f32 v66, v74, v75
	v_cvt_pk_bf16_f32 v67, v76, v77
	v_cvt_pk_bf16_f32 v69, v72, v73
	v_lshl_add_u64 v[70:71], v[70:71], 0, v[116:117]
	global_store_dwordx4 v[70:71], v[66:69], off
	s_nop 1
	v_pk_mul_f32 v[224:225], v[64:65], v[226:227]
	v_exp_f32_e32 v224, v224
	v_exp_f32_e32 v225, v225
	v_pk_mul_f32 v[222:223], v[62:63], v[222:223]
	v_pk_add_f32 v[224:225], v[224:225], v[228:229]
	v_rcp_f32_e32 v224, v224
	v_rcp_f32_e32 v225, v225
	v_pk_mul_f32 v[58:59], v[222:223], v[58:59]
	v_pk_mul_f32 v[222:223], v[54:55], v[226:227]
	v_exp_f32_e32 v222, v222
	v_exp_f32_e32 v223, v223
	v_pk_mul_f32 v[224:225], v[64:65], v[224:225]
	v_pk_add_f32 v[222:223], v[222:223], v[228:229]
	v_rcp_f32_e32 v222, v222
	v_rcp_f32_e32 v223, v223
	v_pk_mul_f32 v[60:61], v[224:225], v[60:61]
	v_pk_mul_f32 v[224:225], v[56:57], v[226:227]
	v_exp_f32_e32 v224, v224
	v_exp_f32_e32 v225, v225
	v_pk_mul_f32 v[222:223], v[54:55], v[222:223]
	v_pk_add_f32 v[224:225], v[224:225], v[228:229]
	v_rcp_f32_e32 v224, v224
	v_rcp_f32_e32 v225, v225
	v_pk_mul_f32 v[54:55], v[222:223], v[50:51]
	v_pk_mul_f32 v[222:223], v[46:47], v[226:227]
	v_exp_f32_e32 v222, v222
	v_exp_f32_e32 v223, v223
	v_pk_mul_f32 v[224:225], v[56:57], v[224:225]
	v_pk_add_f32 v[222:223], v[222:223], v[228:229]
	v_rcp_f32_e32 v222, v222
	v_rcp_f32_e32 v223, v223
	v_pk_mul_f32 v[56:57], v[224:225], v[52:53]
	v_add_u32_e32 v68, 0x80, v145
	v_cvt_pk_bf16_f32 v52, v54, v55
	v_mad_i64_i32 v[54:55], s[20:21], v68, s7, v[114:115]
	v_cvt_pk_bf16_f32 v50, v58, v59
	v_cvt_pk_bf16_f32 v51, v60, v61
	v_cvt_pk_bf16_f32 v53, v56, v57
	v_lshl_add_u64 v[54:55], v[54:55], 0, v[116:117]
	global_store_dwordx4 v[54:55], v[50:53], off
	s_nop 1
	v_pk_mul_f32 v[224:225], v[48:49], v[226:227]
	v_exp_f32_e32 v224, v224
	v_exp_f32_e32 v225, v225
	v_pk_mul_f32 v[222:223], v[46:47], v[222:223]
	v_pk_add_f32 v[224:225], v[224:225], v[228:229]
	v_rcp_f32_e32 v224, v224
	v_rcp_f32_e32 v225, v225
	v_pk_mul_f32 v[42:43], v[222:223], v[42:43]
	v_pk_mul_f32 v[222:223], v[38:39], v[226:227]
	v_exp_f32_e32 v222, v222
	v_exp_f32_e32 v223, v223
	v_pk_mul_f32 v[224:225], v[48:49], v[224:225]
	v_pk_add_f32 v[222:223], v[222:223], v[228:229]
	v_rcp_f32_e32 v222, v222
	v_rcp_f32_e32 v223, v223
	v_pk_mul_f32 v[44:45], v[224:225], v[44:45]
	v_pk_mul_f32 v[224:225], v[40:41], v[226:227]
	v_exp_f32_e32 v224, v224
	v_exp_f32_e32 v225, v225
	v_pk_mul_f32 v[222:223], v[38:39], v[222:223]
	v_pk_add_f32 v[224:225], v[224:225], v[228:229]
	v_rcp_f32_e32 v224, v224
	v_rcp_f32_e32 v225, v225
	v_pk_mul_f32 v[38:39], v[222:223], v[34:35]
	v_pk_mul_f32 v[222:223], v[30:31], v[226:227]
	v_exp_f32_e32 v222, v222
	v_exp_f32_e32 v223, v223
	v_pk_mul_f32 v[224:225], v[40:41], v[224:225]
	v_pk_add_f32 v[222:223], v[222:223], v[228:229]
	v_rcp_f32_e32 v222, v222
	v_rcp_f32_e32 v223, v223
	v_pk_mul_f32 v[40:41], v[224:225], v[36:37]
	v_cvt_pk_bf16_f32 v36, v38, v39
	v_add_u32_e32 v38, 0x90, v145
	v_mad_i64_i32 v[38:39], s[20:21], v38, s7, v[114:115]
	v_cvt_pk_bf16_f32 v34, v42, v43
	v_cvt_pk_bf16_f32 v35, v44, v45
	v_cvt_pk_bf16_f32 v37, v40, v41
	v_lshl_add_u64 v[38:39], v[38:39], 0, v[116:117]
	global_store_dwordx4 v[38:39], v[34:37], off
	s_nop 1
	v_pk_mul_f32 v[224:225], v[32:33], v[226:227]
	v_exp_f32_e32 v224, v224
	v_exp_f32_e32 v225, v225
	v_pk_mul_f32 v[222:223], v[30:31], v[222:223]
	v_pk_add_f32 v[224:225], v[224:225], v[228:229]
	v_rcp_f32_e32 v224, v224
	v_rcp_f32_e32 v225, v225
	v_pk_mul_f32 v[26:27], v[222:223], v[26:27]
	v_pk_mul_f32 v[222:223], v[22:23], v[226:227]
	v_exp_f32_e32 v222, v222
	v_exp_f32_e32 v223, v223
	v_pk_mul_f32 v[224:225], v[32:33], v[224:225]
	v_pk_add_f32 v[222:223], v[222:223], v[228:229]
	v_rcp_f32_e32 v222, v222
	v_rcp_f32_e32 v223, v223
	v_pk_mul_f32 v[28:29], v[224:225], v[28:29]
	v_pk_mul_f32 v[224:225], v[24:25], v[226:227]
	v_exp_f32_e32 v224, v224
	v_exp_f32_e32 v225, v225
	v_pk_mul_f32 v[222:223], v[22:23], v[222:223]
	v_pk_add_f32 v[224:225], v[224:225], v[228:229]
	v_rcp_f32_e32 v224, v224
	v_rcp_f32_e32 v225, v225
	v_pk_mul_f32 v[22:23], v[222:223], v[18:19]
	v_pk_mul_f32 v[222:223], v[14:15], v[226:227]
	v_exp_f32_e32 v222, v222
	v_exp_f32_e32 v223, v223
	v_pk_mul_f32 v[224:225], v[24:25], v[224:225]
	v_pk_add_f32 v[222:223], v[222:223], v[228:229]
	v_rcp_f32_e32 v222, v222
	v_rcp_f32_e32 v223, v223
	v_pk_mul_f32 v[24:25], v[224:225], v[20:21]
	v_cvt_pk_bf16_f32 v20, v22, v23
	v_add_u32_e32 v22, 0xa0, v145
	v_mad_i64_i32 v[22:23], s[20:21], v22, s7, v[114:115]
	v_cvt_pk_bf16_f32 v18, v26, v27
	v_cvt_pk_bf16_f32 v19, v28, v29
	v_cvt_pk_bf16_f32 v21, v24, v25
	v_lshl_add_u64 v[22:23], v[22:23], 0, v[116:117]
	global_store_dwordx4 v[22:23], v[18:21], off
	s_nop 1
	v_pk_mul_f32 v[224:225], v[16:17], v[226:227]
	v_exp_f32_e32 v224, v224
	v_exp_f32_e32 v225, v225
	v_pk_mul_f32 v[222:223], v[14:15], v[222:223]
	v_pk_add_f32 v[224:225], v[224:225], v[228:229]
	v_rcp_f32_e32 v224, v224
	v_rcp_f32_e32 v225, v225
	v_pk_mul_f32 v[10:11], v[222:223], v[10:11]
	v_pk_mul_f32 v[222:223], v[6:7], v[226:227]
	v_exp_f32_e32 v222, v222
	v_exp_f32_e32 v223, v223
	v_pk_mul_f32 v[224:225], v[16:17], v[224:225]
	v_pk_add_f32 v[222:223], v[222:223], v[228:229]
	v_rcp_f32_e32 v222, v222
	v_rcp_f32_e32 v223, v223
	v_pk_mul_f32 v[12:13], v[224:225], v[12:13]
	v_pk_mul_f32 v[224:225], v[8:9], v[226:227]
	v_exp_f32_e32 v224, v224
	v_exp_f32_e32 v225, v225
	v_pk_mul_f32 v[222:223], v[6:7], v[222:223]
	v_pk_add_f32 v[224:225], v[224:225], v[228:229]
	v_rcp_f32_e32 v224, v224
	v_rcp_f32_e32 v225, v225
	v_pk_mul_f32 v[6:7], v[222:223], v[2:3]
	v_pk_mul_f32 v[224:225], v[8:9], v[224:225]
	v_pk_mul_f32 v[8:9], v[224:225], v[4:5]
	v_cvt_pk_bf16_f32 v4, v6, v7
	v_add_u32_e32 v6, 0xb0, v145
	v_mad_i64_i32 v[6:7], s[20:21], v6, s7, v[114:115]
	v_cvt_pk_bf16_f32 v2, v10, v11
	v_cvt_pk_bf16_f32 v3, v12, v13
	v_cvt_pk_bf16_f32 v5, v8, v9
	v_lshl_add_u64 v[6:7], v[6:7], 0, v[116:117]
	s_mov_b64 s[20:21], s[12:13]
	global_store_dwordx4 v[6:7], v[2:5], off
	s_cbranch_vccz .LBB0_294
	s_waitcnt vmcnt(0)
	s_cmpk_gt_u32 s28, 0xff
	s_cbranch_scc1 .LBB0_301
	s_barrier
